# c2 + P5: waves 0-3 start epilogue without waiting for waves 4-7 last MFMA block (exit barrier pair removed)
# baseline (speedup 1.0000x reference)
.LBB0_872:
	v_add_u32_e32 v162, s73, v140
	v_add_u32_e32 v178, s74, v140
	ds_read_b128 v[150:153], v162
	ds_read_b128 v[154:157], v162 offset:1024
	ds_read_b128 v[158:161], v162 offset:2048
	ds_read_b128 v[162:165], v162 offset:3072
	ds_read_b128 v[166:169], v178
	ds_read_b128 v[170:173], v178 offset:1024
	ds_read_b128 v[174:177], v178 offset:2048
	ds_read_b128 v[178:181], v178 offset:3072
	s_add_i32 s77, s52, 2
	s_add_u32 s50, s34, 0xfffc0080
	s_addc_u32 s51, s35, -1
	s_cmp_eq_u32 s70, s52
	s_cselect_b32 s52, s30, s21
	s_cselect_b32 s55, s29, s51
	s_cselect_b32 s54, s28, s50
	s_cselect_b32 s53, s31, s23
	v_lshl_add_u64 v[214:215], s[34:35], 0, v[132:133]
	s_add_i32 m0, s60, 0xc000
	ds_read_b128 v[182:185], v149
	ds_read_b128 v[186:189], v149 offset:1024
	ds_read_b128 v[190:193], v149 offset:2048
	ds_read_b128 v[194:197], v149 offset:3072
	ds_read_b128 v[198:201], v149 offset:4096
	ds_read_b128 v[202:205], v149 offset:5120
	ds_read_b128 v[206:209], v149 offset:6144
	ds_read_b128 v[210:213], v149 offset:7168
	global_load_lds_dwordx4 v[214:215], off
	v_lshl_add_u64 v[214:215], s[34:35], 0, v[134:135]
	s_add_i32 m0, s60, 0xe000
	s_nop 0
	global_load_lds_dwordx4 v[214:215], off
	s_waitcnt vmcnt(8)
	s_waitcnt lgkmcnt(0)
	s_barrier
	v_mfma_f32_16x16x32_bf16 v[78:81], v[150:153], v[182:185], v[78:81]
	v_mfma_f32_16x16x32_bf16 v[14:17], v[158:161], v[182:185], v[14:17]
	v_mfma_f32_16x16x32_bf16 v[66:69], v[150:153], v[190:193], v[66:69]
	v_mfma_f32_16x16x32_bf16 v[2:5], v[158:161], v[190:193], v[2:5]
	v_mfma_f32_16x16x32_bf16 v[70:73], v[150:153], v[198:201], v[70:73]
	v_mfma_f32_16x16x32_bf16 v[6:9], v[158:161], v[198:201], v[6:9]
	v_mfma_f32_16x16x32_bf16 v[74:77], v[150:153], v[206:209], v[74:77]
	v_mfma_f32_16x16x32_bf16 v[10:13], v[158:161], v[206:209], v[10:13]
	v_mfma_f32_16x16x32_bf16 v[78:81], v[154:157], v[186:189], v[78:81]
	v_mfma_f32_16x16x32_bf16 v[14:17], v[162:165], v[186:189], v[14:17]
	v_mfma_f32_16x16x32_bf16 v[66:69], v[154:157], v[194:197], v[66:69]
	v_mfma_f32_16x16x32_bf16 v[2:5], v[162:165], v[194:197], v[2:5]
	v_mfma_f32_16x16x32_bf16 v[70:73], v[154:157], v[202:205], v[70:73]
	v_mfma_f32_16x16x32_bf16 v[6:9], v[162:165], v[202:205], v[6:9]
	v_mfma_f32_16x16x32_bf16 v[74:77], v[154:157], v[210:213], v[74:77]
	v_mfma_f32_16x16x32_bf16 v[10:13], v[162:165], v[210:213], v[10:13]
	v_mfma_f32_16x16x32_bf16 v[98:101], v[166:169], v[182:185], v[98:101]
	v_mfma_f32_16x16x32_bf16 v[34:37], v[174:177], v[182:185], v[34:37]
	v_mfma_f32_16x16x32_bf16 v[82:85], v[166:169], v[190:193], v[82:85]
	v_mfma_f32_16x16x32_bf16 v[18:21], v[174:177], v[190:193], v[18:21]
	v_mfma_f32_16x16x32_bf16 v[86:89], v[166:169], v[198:201], v[86:89]
	v_mfma_f32_16x16x32_bf16 v[22:25], v[174:177], v[198:201], v[22:25]
	v_mfma_f32_16x16x32_bf16 v[94:97], v[166:169], v[206:209], v[94:97]
	v_mfma_f32_16x16x32_bf16 v[30:33], v[174:177], v[206:209], v[30:33]
	v_mfma_f32_16x16x32_bf16 v[98:101], v[170:173], v[186:189], v[98:101]
	v_mfma_f32_16x16x32_bf16 v[34:37], v[178:181], v[186:189], v[34:37]
	v_mfma_f32_16x16x32_bf16 v[82:85], v[170:173], v[194:197], v[82:85]
	v_mfma_f32_16x16x32_bf16 v[18:21], v[178:181], v[194:197], v[18:21]
	v_mfma_f32_16x16x32_bf16 v[86:89], v[170:173], v[202:205], v[86:89]
	v_mfma_f32_16x16x32_bf16 v[22:25], v[178:181], v[202:205], v[22:25]
	v_mfma_f32_16x16x32_bf16 v[94:97], v[170:173], v[210:213], v[94:97]
	v_mfma_f32_16x16x32_bf16 v[30:33], v[178:181], v[210:213], v[30:33]
	s_barrier
	s_add_i32 s50, s73, s15
	v_lshl_add_u64 v[214:215], s[52:53], 0, v[228:229]
	s_mov_b32 m0, s50
	ds_read_b128 v[182:185], v149 offset:16384
	ds_read_b128 v[186:189], v149 offset:17408
	ds_read_b128 v[190:193], v149 offset:18432
	ds_read_b128 v[194:197], v149 offset:19456
	ds_read_b128 v[198:201], v149 offset:20480
	ds_read_b128 v[202:205], v149 offset:21504
	ds_read_b128 v[206:209], v149 offset:22528
	ds_read_b128 v[210:213], v149 offset:23552
	global_load_lds_dwordx4 v[214:215], off
	s_add_i32 m0, s50, 0x2000
	s_add_u32 s50, s52, 0x40000
	v_lshl_add_u64 v[216:217], s[52:53], 0, v[232:233]
	s_addc_u32 s51, s53, 0
	s_add_i32 s78, s74, s15
	global_load_lds_dwordx4 v[216:217], off
	v_lshl_add_u64 v[218:219], s[50:51], 0, v[228:229]
	s_mov_b32 m0, s78
	v_lshl_add_u64 v[220:221], s[54:55], 0, v[230:231]
	global_load_lds_dwordx4 v[218:219], off
	v_lshl_add_u64 v[218:219], s[50:51], 0, v[232:233]
	s_add_i32 m0, s78, 0x2000
	s_nop 0
	global_load_lds_dwordx4 v[218:219], off
	v_lshl_add_u64 v[218:219], s[54:55], 0, v[226:227]
	s_mov_b32 m0, s60
	s_nop 0
	global_load_lds_dwordx4 v[218:219], off
	s_mov_b32 m0, s61
	s_nop 0
	global_load_lds_dwordx4 v[220:221], off
	s_waitcnt vmcnt(8)
	s_waitcnt lgkmcnt(0)
	s_barrier
	v_mfma_f32_16x16x32_bf16 v[90:93], v[150:153], v[182:185], v[90:93]
	v_mfma_f32_16x16x32_bf16 v[26:29], v[158:161], v[182:185], v[26:29]
	v_mfma_f32_16x16x32_bf16 v[102:105], v[150:153], v[190:193], v[102:105]
	v_mfma_f32_16x16x32_bf16 v[38:41], v[158:161], v[190:193], v[38:41]
	v_mfma_f32_16x16x32_bf16 v[106:109], v[150:153], v[198:201], v[106:109]
	v_mfma_f32_16x16x32_bf16 v[42:45], v[158:161], v[198:201], v[42:45]
	v_mfma_f32_16x16x32_bf16 v[110:113], v[150:153], v[206:209], v[110:113]
	v_mfma_f32_16x16x32_bf16 v[46:49], v[158:161], v[206:209], v[46:49]
	v_mfma_f32_16x16x32_bf16 v[90:93], v[154:157], v[186:189], v[90:93]
	v_mfma_f32_16x16x32_bf16 v[26:29], v[162:165], v[186:189], v[26:29]
	v_mfma_f32_16x16x32_bf16 v[102:105], v[154:157], v[194:197], v[102:105]
	v_mfma_f32_16x16x32_bf16 v[38:41], v[162:165], v[194:197], v[38:41]
	v_mfma_f32_16x16x32_bf16 v[106:109], v[154:157], v[202:205], v[106:109]
	v_mfma_f32_16x16x32_bf16 v[42:45], v[162:165], v[202:205], v[42:45]
	v_mfma_f32_16x16x32_bf16 v[110:113], v[154:157], v[210:213], v[110:113]
	v_mfma_f32_16x16x32_bf16 v[46:49], v[162:165], v[210:213], v[46:49]
	v_mfma_f32_16x16x32_bf16 v[114:117], v[166:169], v[182:185], v[114:117]
	v_mfma_f32_16x16x32_bf16 v[50:53], v[174:177], v[182:185], v[50:53]
	v_mfma_f32_16x16x32_bf16 v[118:121], v[166:169], v[190:193], v[118:121]
	v_mfma_f32_16x16x32_bf16 v[54:57], v[174:177], v[190:193], v[54:57]
	v_mfma_f32_16x16x32_bf16 v[122:125], v[166:169], v[198:201], v[122:125]
	v_mfma_f32_16x16x32_bf16 v[58:61], v[174:177], v[198:201], v[58:61]
	v_mfma_f32_16x16x32_bf16 v[126:129], v[166:169], v[206:209], v[126:129]
	v_mfma_f32_16x16x32_bf16 v[62:65], v[174:177], v[206:209], v[62:65]
	v_mfma_f32_16x16x32_bf16 v[114:117], v[170:173], v[186:189], v[114:117]
	v_mfma_f32_16x16x32_bf16 v[50:53], v[178:181], v[186:189], v[50:53]
	v_mfma_f32_16x16x32_bf16 v[118:121], v[170:173], v[194:197], v[118:121]
	v_mfma_f32_16x16x32_bf16 v[54:57], v[178:181], v[194:197], v[54:57]
	v_mfma_f32_16x16x32_bf16 v[122:125], v[170:173], v[202:205], v[122:125]
	v_mfma_f32_16x16x32_bf16 v[58:61], v[178:181], v[202:205], v[58:61]
	v_mfma_f32_16x16x32_bf16 v[126:129], v[170:173], v[210:213], v[126:129]
	v_mfma_f32_16x16x32_bf16 v[62:65], v[178:181], v[210:213], v[62:65]
	s_barrier
	s_add_i32 s78, 0, 0x18000
	s_add_i32 s79, 0, 0x1c000
	v_add_u32_e32 v162, s78, v140
	v_add_u32_e32 v178, s79, v140
	ds_read_b128 v[150:153], v162
	ds_read_b128 v[154:157], v162 offset:1024
	ds_read_b128 v[158:161], v162 offset:2048
	ds_read_b128 v[162:165], v162 offset:3072
	ds_read_b128 v[166:169], v178
	ds_read_b128 v[170:173], v178 offset:1024
	ds_read_b128 v[174:177], v178 offset:2048
	ds_read_b128 v[178:181], v178 offset:3072
	s_add_u32 s50, s54, 0x40000
	s_addc_u32 s51, s55, 0
	s_mov_b32 m0, s62
	v_lshl_add_u64 v[222:223], s[50:51], 0, v[226:227]
	ds_read_b128 v[182:185], v149 offset:32768
	ds_read_b128 v[186:189], v149 offset:33792
	ds_read_b128 v[190:193], v149 offset:34816
	ds_read_b128 v[194:197], v149 offset:35840
	ds_read_b128 v[198:201], v149 offset:36864
	ds_read_b128 v[202:205], v149 offset:37888
	ds_read_b128 v[206:209], v149 offset:38912
	ds_read_b128 v[210:213], v149 offset:39936
	global_load_lds_dwordx4 v[222:223], off
	v_lshl_add_u64 v[222:223], s[50:51], 0, v[230:231]
	s_mov_b32 m0, s63
	s_nop 0
	global_load_lds_dwordx4 v[222:223], off
	s_waitcnt vmcnt(8)
	s_waitcnt lgkmcnt(0)
	s_barrier
	v_mfma_f32_16x16x32_bf16 v[78:81], v[150:153], v[182:185], v[78:81]
	v_mfma_f32_16x16x32_bf16 v[14:17], v[158:161], v[182:185], v[14:17]
	v_mfma_f32_16x16x32_bf16 v[66:69], v[150:153], v[190:193], v[66:69]
	v_mfma_f32_16x16x32_bf16 v[2:5], v[158:161], v[190:193], v[2:5]
	v_mfma_f32_16x16x32_bf16 v[70:73], v[150:153], v[198:201], v[70:73]
	v_mfma_f32_16x16x32_bf16 v[6:9], v[158:161], v[198:201], v[6:9]
	v_mfma_f32_16x16x32_bf16 v[74:77], v[150:153], v[206:209], v[74:77]
	v_mfma_f32_16x16x32_bf16 v[10:13], v[158:161], v[206:209], v[10:13]
	v_mfma_f32_16x16x32_bf16 v[78:81], v[154:157], v[186:189], v[78:81]
	v_mfma_f32_16x16x32_bf16 v[14:17], v[162:165], v[186:189], v[14:17]
	v_mfma_f32_16x16x32_bf16 v[66:69], v[154:157], v[194:197], v[66:69]
	v_mfma_f32_16x16x32_bf16 v[2:5], v[162:165], v[194:197], v[2:5]
	v_mfma_f32_16x16x32_bf16 v[70:73], v[154:157], v[202:205], v[70:73]
	v_mfma_f32_16x16x32_bf16 v[6:9], v[162:165], v[202:205], v[6:9]
	v_mfma_f32_16x16x32_bf16 v[74:77], v[154:157], v[210:213], v[74:77]
	v_mfma_f32_16x16x32_bf16 v[10:13], v[162:165], v[210:213], v[10:13]
	v_mfma_f32_16x16x32_bf16 v[98:101], v[166:169], v[182:185], v[98:101]
	v_mfma_f32_16x16x32_bf16 v[34:37], v[174:177], v[182:185], v[34:37]
	v_mfma_f32_16x16x32_bf16 v[82:85], v[166:169], v[190:193], v[82:85]
	v_mfma_f32_16x16x32_bf16 v[18:21], v[174:177], v[190:193], v[18:21]
	v_mfma_f32_16x16x32_bf16 v[86:89], v[166:169], v[198:201], v[86:89]
	v_mfma_f32_16x16x32_bf16 v[22:25], v[174:177], v[198:201], v[22:25]
	v_mfma_f32_16x16x32_bf16 v[94:97], v[166:169], v[206:209], v[94:97]
	v_mfma_f32_16x16x32_bf16 v[30:33], v[174:177], v[206:209], v[30:33]
	v_mfma_f32_16x16x32_bf16 v[98:101], v[170:173], v[186:189], v[98:101]
	v_mfma_f32_16x16x32_bf16 v[34:37], v[178:181], v[186:189], v[34:37]
	v_mfma_f32_16x16x32_bf16 v[82:85], v[170:173], v[194:197], v[82:85]
	v_mfma_f32_16x16x32_bf16 v[18:21], v[178:181], v[194:197], v[18:21]
	v_mfma_f32_16x16x32_bf16 v[86:89], v[170:173], v[202:205], v[86:89]
	v_mfma_f32_16x16x32_bf16 v[22:25], v[178:181], v[202:205], v[22:25]
	v_mfma_f32_16x16x32_bf16 v[94:97], v[170:173], v[210:213], v[94:97]
	v_mfma_f32_16x16x32_bf16 v[30:33], v[178:181], v[210:213], v[30:33]
	s_barrier
	s_add_i32 s50, s78, s15
	v_lshl_add_u64 v[214:215], v[214:215], 0, s[8:9]
	s_mov_b32 m0, s50
	ds_read_b128 v[182:185], v149 offset:49152
	ds_read_b128 v[186:189], v149 offset:50176
	ds_read_b128 v[190:193], v149 offset:51200
	ds_read_b128 v[194:197], v149 offset:52224
	ds_read_b128 v[198:201], v149 offset:53248
	ds_read_b128 v[202:205], v149 offset:54272
	ds_read_b128 v[206:209], v149 offset:55296
	ds_read_b128 v[210:213], v149 offset:56320
	global_load_lds_dwordx4 v[214:215], off
	s_add_i32 m0, s50, 0x2000
	s_add_u32 s50, s52, 0x40080
	v_lshl_add_u64 v[214:215], v[216:217], 0, s[8:9]
	s_addc_u32 s51, s53, 0
	s_add_i32 s52, s79, s15
	global_load_lds_dwordx4 v[214:215], off
	v_lshl_add_u64 v[214:215], s[50:51], 0, v[228:229]
	s_mov_b32 m0, s52
	s_nop 0
	global_load_lds_dwordx4 v[214:215], off
	v_lshl_add_u64 v[214:215], s[50:51], 0, v[232:233]
	s_add_i32 m0, s52, 0x2000
	s_nop 0
	global_load_lds_dwordx4 v[214:215], off
	v_lshl_add_u64 v[214:215], v[218:219], 0, s[8:9]
	s_mov_b32 m0, s68
	s_nop 0
	global_load_lds_dwordx4 v[214:215], off
	v_lshl_add_u64 v[214:215], v[220:221], 0, s[8:9]
	s_mov_b32 m0, s69
	s_nop 0
	global_load_lds_dwordx4 v[214:215], off
	s_waitcnt vmcnt(8)
	s_waitcnt lgkmcnt(0)
	s_barrier
	v_mfma_f32_16x16x32_bf16 v[90:93], v[150:153], v[182:185], v[90:93]
	v_mfma_f32_16x16x32_bf16 v[26:29], v[158:161], v[182:185], v[26:29]
	v_mfma_f32_16x16x32_bf16 v[102:105], v[150:153], v[190:193], v[102:105]
	v_mfma_f32_16x16x32_bf16 v[38:41], v[158:161], v[190:193], v[38:41]
	v_mfma_f32_16x16x32_bf16 v[106:109], v[150:153], v[198:201], v[106:109]
	v_mfma_f32_16x16x32_bf16 v[42:45], v[158:161], v[198:201], v[42:45]
	v_mfma_f32_16x16x32_bf16 v[110:113], v[150:153], v[206:209], v[110:113]
	v_mfma_f32_16x16x32_bf16 v[46:49], v[158:161], v[206:209], v[46:49]
	v_mfma_f32_16x16x32_bf16 v[90:93], v[154:157], v[186:189], v[90:93]
	v_mfma_f32_16x16x32_bf16 v[26:29], v[162:165], v[186:189], v[26:29]
	v_mfma_f32_16x16x32_bf16 v[102:105], v[154:157], v[194:197], v[102:105]
	v_mfma_f32_16x16x32_bf16 v[38:41], v[162:165], v[194:197], v[38:41]
	v_mfma_f32_16x16x32_bf16 v[106:109], v[154:157], v[202:205], v[106:109]
	v_mfma_f32_16x16x32_bf16 v[42:45], v[162:165], v[202:205], v[42:45]
	v_mfma_f32_16x16x32_bf16 v[110:113], v[154:157], v[210:213], v[110:113]
	v_mfma_f32_16x16x32_bf16 v[46:49], v[162:165], v[210:213], v[46:49]
	v_mfma_f32_16x16x32_bf16 v[114:117], v[166:169], v[182:185], v[114:117]
	v_mfma_f32_16x16x32_bf16 v[50:53], v[174:177], v[182:185], v[50:53]
	v_mfma_f32_16x16x32_bf16 v[118:121], v[166:169], v[190:193], v[118:121]
	v_mfma_f32_16x16x32_bf16 v[54:57], v[174:177], v[190:193], v[54:57]
	v_mfma_f32_16x16x32_bf16 v[122:125], v[166:169], v[198:201], v[122:125]
	v_mfma_f32_16x16x32_bf16 v[58:61], v[174:177], v[198:201], v[58:61]
	v_mfma_f32_16x16x32_bf16 v[126:129], v[166:169], v[206:209], v[126:129]
	v_mfma_f32_16x16x32_bf16 v[62:65], v[174:177], v[206:209], v[62:65]
	v_mfma_f32_16x16x32_bf16 v[114:117], v[170:173], v[186:189], v[114:117]
	v_mfma_f32_16x16x32_bf16 v[50:53], v[178:181], v[186:189], v[50:53]
	v_mfma_f32_16x16x32_bf16 v[118:121], v[170:173], v[194:197], v[118:121]
	v_mfma_f32_16x16x32_bf16 v[54:57], v[178:181], v[194:197], v[54:57]
	v_mfma_f32_16x16x32_bf16 v[122:125], v[170:173], v[202:205], v[122:125]
	v_mfma_f32_16x16x32_bf16 v[58:61], v[178:181], v[202:205], v[58:61]
	v_mfma_f32_16x16x32_bf16 v[126:129], v[170:173], v[210:213], v[126:129]
	v_mfma_f32_16x16x32_bf16 v[62:65], v[178:181], v[210:213], v[62:65]
	s_add_u32 s34, s34, 0x100
	s_addc_u32 s35, s35, 0
	s_add_u32 s21, s21, 0x100
	s_addc_u32 s23, s23, 0
	s_cmp_ge_i32 s77, s66
	s_mov_b32 s52, s77
	s_cbranch_scc1 .LBB0_873
	s_barrier
	s_branch .LBB0_872
